# MLA prompt loop: 32 v_pk_add_f32 split into scalar v_add_f32 pairs (bit-identical row sums)
# speedup vs baseline: 1.0134x; 1.0119x over previous
; DI float ex2(float x) { return __builtin_amdgcn_exp2f(x); }
; #define MFMA32(a, b, c) __builtin_amdgcn_mfma_f32_32x32x16_bf16((a), (b), (c), 0, 0, 0)
; DI void mla_item(const P& p, char* smem, int b, int hd, int q0, bool samp) {
;     ...
;       const char* Kt = smem + (kb & 1) * STG + hoff; const char* Vt = Kt + 64 * KS_MLA;
;       f32x16 s[2];
;       const float cinit = (kb == 0) ? 0.f : -mrun;
; #pragma unroll
;       for (int i = 0; i < 16; ++i) { s[0][i] = cinit; s[1][i] = cinit; }
;       const char* kp = Kt + l32 * KS_MLA + lh * 16;
; #pragma unroll
;       for (int ks = 0; ks < 6; ++ks) {
;         const bf16x8 a0 = *(const bf16x8*)(kp + ks * 32);
;         const bf16x8 a1 = *(const bf16x8*)(kp + 32 * KS_MLA + ks * 32);
;         s[0] = MFMA32(a0, qf[ks], s[0]);
;         s[1] = MFMA32(a1, qf[ks], s[1]);
;       }
;       f32x16 e[2];
;       float ps0 = 0.f, ps1 = 0.f;
;       bool redo = (kb == 0);
;       if (!redo) {
; #pragma unroll
;         for (int i = 0; i < 16; ++i) { e[0][i] = ex2(s[0][i]); e[1][i] = ex2(s[1][i]); ps0 += e[0][i]; ps1 += e[1][i]; }
;         redo = (__builtin_amdgcn_ballot_w64(!(ps0 + ps1 < 1e18f)) != 0ull);
;       }
.LBB0_413:
	s_or_b64 exec, exec, s[6:7]
	s_add_i32 s6, s46, -1
	s_cmp_gt_i32 s6, s60
	s_cbranch_scc1 .LBB0_418
	s_bitcmp1_b32 s6, 0
	s_cselect_b32 s6, 0xc800, 0
	s_add_i32 s6, s6, 16
	v_add3_u32 v1, s6, v160, v106
	ds_read_b128 v[112:115], v1
	ds_read_b128 v[116:119], v1 offset:32
	v_xor_b32_e32 v36, 0x80000000, v161
	v_mov_b32_e32 v37, v36
	v_mov_b32_e32 v38, v36
	v_mov_b32_e32 v39, v36
	v_mov_b32_e32 v40, v36
	v_mov_b32_e32 v41, v36
	v_mov_b32_e32 v42, v36
	v_mov_b32_e32 v43, v36
	v_mov_b32_e32 v44, v36
	v_mov_b32_e32 v45, v36
	v_mov_b32_e32 v46, v36
	v_mov_b32_e32 v47, v36
	v_mov_b32_e32 v48, v36
	v_mov_b32_e32 v49, v36
	v_mov_b32_e32 v50, v36
	v_mov_b32_e32 v51, v36
	s_waitcnt lgkmcnt(1)
	s_nop 0
	v_mfma_f32_32x32x16_bf16 v[52:67], v[112:115], v[88:91], v[36:51]
	ds_read_b128 v[112:115], v1 offset:6656
	ds_read_b128 v[120:123], v1 offset:6688
	s_waitcnt lgkmcnt(1)
	v_mfma_f32_32x32x16_bf16 v[36:51], v[112:115], v[88:91], v[36:51]
	v_mfma_f32_32x32x16_bf16 v[52:67], v[116:119], v[84:87], v[52:67]
	ds_read_b128 v[112:115], v1 offset:64
	ds_read_b128 v[116:119], v1 offset:96
	s_waitcnt lgkmcnt(2)
	v_mfma_f32_32x32x16_bf16 v[36:51], v[120:123], v[84:87], v[36:51]
	s_waitcnt lgkmcnt(1)
	v_mfma_f32_32x32x16_bf16 v[52:67], v[112:115], v[80:83], v[52:67]
	ds_read_b128 v[112:115], v1 offset:6720
	ds_read_b128 v[120:123], v1 offset:6752
	s_waitcnt lgkmcnt(1)
	v_mfma_f32_32x32x16_bf16 v[36:51], v[112:115], v[80:83], v[36:51]
	v_mfma_f32_32x32x16_bf16 v[52:67], v[116:119], v[76:79], v[52:67]
	ds_read_b128 v[112:115], v1 offset:128
	ds_read_b128 v[116:119], v1 offset:160
	s_waitcnt lgkmcnt(2)
	v_mfma_f32_32x32x16_bf16 v[36:51], v[120:123], v[76:79], v[36:51]
	s_waitcnt lgkmcnt(1)
	v_mfma_f32_32x32x16_bf16 v[52:67], v[112:115], v[72:75], v[52:67]
	ds_read_b128 v[112:115], v1 offset:6784
	ds_read_b128 v[120:123], v1 offset:6816
	s_waitcnt lgkmcnt(1)
	v_mfma_f32_32x32x16_bf16 v[36:51], v[112:115], v[72:75], v[36:51]
	v_mfma_f32_32x32x16_bf16 v[52:67], v[116:119], v[68:71], v[52:67]
	s_waitcnt lgkmcnt(0)
	v_mfma_f32_32x32x16_bf16 v[36:51], v[120:123], v[68:71], v[36:51]
	s_nop 9
	v_exp_f32_e32 v112, v52
	v_exp_f32_e32 v114, v53
	v_exp_f32_e32 v116, v54
	v_exp_f32_e32 v118, v55
	v_exp_f32_e32 v120, v56
	v_exp_f32_e32 v122, v57
	v_exp_f32_e32 v138, v58
	v_exp_f32_e32 v113, v36
	v_exp_f32_e32 v115, v37
	v_exp_f32_e32 v117, v38
	v_exp_f32_e32 v119, v39
	v_exp_f32_e32 v121, v40
	v_add_f32_e32 v124, 0, v112
	v_add_f32_e32 v125, 0, v113
	v_exp_f32_e32 v123, v41
	v_add_f32_e32 v124, v114, v124
	v_add_f32_e32 v125, v115, v125
	v_exp_f32_e32 v139, v42
	v_add_f32_e32 v124, v116, v124
	v_add_f32_e32 v125, v117, v125
	v_exp_f32_e32 v140, v59
	v_add_f32_e32 v124, v118, v124
	v_add_f32_e32 v125, v119, v125
	v_exp_f32_e32 v141, v43
	v_add_f32_e32 v124, v120, v124
	v_add_f32_e32 v125, v121, v125
	v_exp_f32_e32 v126, v61
	v_add_f32_e32 v142, v122, v124
	v_add_f32_e32 v143, v123, v125
	v_exp_f32_e32 v124, v60
	v_exp_f32_e32 v125, v44
	v_exp_f32_e32 v127, v45
	v_exp_f32_e32 v128, v62
	v_exp_f32_e32 v129, v46
	v_add_f32_e32 v142, v138, v142
	v_add_f32_e32 v143, v139, v143
	v_exp_f32_e32 v130, v63
	v_exp_f32_e32 v131, v47
	v_add_f32_e32 v142, v140, v142
	v_add_f32_e32 v143, v141, v143
	v_exp_f32_e32 v132, v64
	v_exp_f32_e32 v133, v48
	v_add_f32_e32 v142, v124, v142
	v_add_f32_e32 v143, v125, v143
	v_exp_f32_e32 v134, v65
	v_exp_f32_e32 v135, v49
	v_add_f32_e32 v142, v126, v142
	v_add_f32_e32 v143, v127, v143
	v_exp_f32_e32 v136, v66
	v_exp_f32_e32 v137, v50
	v_add_f32_e32 v142, v128, v142
	v_add_f32_e32 v143, v129, v143
	v_exp_f32_e32 v144, v67
	v_exp_f32_e32 v145, v51
	v_add_f32_e32 v142, v130, v142
	v_add_f32_e32 v143, v131, v143
	s_nop 0
	v_add_f32_e32 v142, v132, v142
	v_add_f32_e32 v143, v133, v143
	s_nop 0
	v_add_f32_e32 v142, v134, v142
	v_add_f32_e32 v143, v135, v143
	s_nop 0
	v_add_f32_e32 v142, v136, v142
	v_add_f32_e32 v143, v137, v143
	s_nop 0
	v_add_f32_e32 v142, v144, v142
	v_add_f32_e32 v143, v145, v143
	s_nop 0
	v_add_f32_e32 v1, v142, v143
	v_cmp_ngt_f32_e32 vcc, s79, v1
	s_cbranch_vccz .LBB0_416
; DI float ex2(float x) { return __builtin_amdgcn_exp2f(x); }
; DI void mla_item(const P& p, char* smem, int b, int hd, int q0, bool samp) {
;     ...
;       if (redo) {
;         float mx = fmaxf(s[0][0], s[1][0]);
; #pragma unroll
;         for (int i = 1; i < 16; ++i) mx = fmaxf(mx, fmaxf(s[0][i], s[1][i]));
;         mx = fmaxf(mx, __shfl_xor(mx, 32));
;         const float up = (kb == 0) ? mx : fmaxf(mx, 0.f);
;         const float alpha = (kb == 0) ? 0.f : ex2(-up);
;         lsum *= alpha;
; #pragma unroll
;         for (int i = 0; i < 16; ++i) { o[0][i] *= alpha; o[1][i] *= alpha; }
;         mrun = (kb == 0) ? mx : mrun + up;
;         ps0 = 0.f; ps1 = 0.f;
; #pragma unroll
;         for (int i = 0; i < 16; ++i) { e[0][i] = ex2(s[0][i] - up); e[1][i] = ex2(s[1][i] - up); ps0 += e[0][i]; ps1 += e[1][i]; }
;       }
;       lsum += ps0 + ps1;
	v_max_f32_e32 v1, v37, v37
	v_max_f32_e32 v2, v53, v53
	v_max_f32_e32 v1, v2, v1
	v_max_f32_e32 v2, v38, v38
	v_max_f32_e32 v112, v54, v54
	v_max_f32_e32 v2, v112, v2
	v_max_f32_e32 v112, v39, v39
	v_max_f32_e32 v113, v55, v55
	v_max3_f32 v1, v52, v36, v1
	v_max_f32_e32 v112, v113, v112
	v_max3_f32 v1, v1, v2, v112
	v_max_f32_e32 v2, v40, v40
	v_max_f32_e32 v112, v56, v56
	v_max_f32_e32 v2, v112, v2
	v_max_f32_e32 v112, v41, v41
	v_max_f32_e32 v113, v57, v57
	v_max_f32_e32 v112, v113, v112
	v_max3_f32 v1, v1, v2, v112
	v_max_f32_e32 v2, v42, v42
	v_max_f32_e32 v112, v58, v58
	v_max_f32_e32 v2, v112, v2
	v_max_f32_e32 v112, v43, v43
	v_max_f32_e32 v113, v59, v59
	v_max_f32_e32 v112, v113, v112
	v_max3_f32 v1, v1, v2, v112
	v_max_f32_e32 v2, v44, v44
	v_max_f32_e32 v112, v60, v60
	v_max_f32_e32 v2, v112, v2
	v_max_f32_e32 v112, v45, v45
	v_max_f32_e32 v113, v61, v61
	v_max_f32_e32 v112, v113, v112
	v_max3_f32 v1, v1, v2, v112
	v_max_f32_e32 v2, v46, v46
	v_max_f32_e32 v112, v62, v62
	v_max_f32_e32 v2, v112, v2
	v_max_f32_e32 v112, v47, v47
	v_max_f32_e32 v113, v63, v63
	v_max_f32_e32 v112, v113, v112
	v_max3_f32 v1, v1, v2, v112
	v_max_f32_e32 v2, v48, v48
	v_max_f32_e32 v112, v64, v64
	v_max_f32_e32 v2, v112, v2
	v_max_f32_e32 v112, v49, v49
	v_max_f32_e32 v113, v65, v65
	v_max_f32_e32 v112, v113, v112
	v_max3_f32 v1, v1, v2, v112
	v_max_f32_e32 v2, v50, v50
	v_max_f32_e32 v112, v66, v66
	v_max_f32_e32 v2, v112, v2
	v_max_f32_e32 v112, v51, v51
	v_max_f32_e32 v113, v67, v67
	v_max_f32_e32 v112, v113, v112
	v_max3_f32 v1, v1, v2, v112
	v_and_b32_e32 v112, 64, v154
	v_xor_b32_e32 v2, 32, v154
	v_add_u32_e32 v112, 64, v112
	v_cmp_lt_i32_e32 vcc, v2, v112
	s_nop 1
	v_cndmask_b32_e32 v2, v154, v2, vcc
	v_lshlrev_b32_e32 v2, 2, v2
	ds_bpermute_b32 v2, v2, v1
	s_waitcnt lgkmcnt(0)
	v_max3_f32 v1, v1, v2, 0
	v_sub_f32_e32 v2, v52, v1
	v_exp_f32_e32 v112, v2
	v_sub_f32_e32 v2, v36, v1
	v_exp_f32_e32 v113, v2
	v_sub_f32_e32 v2, v53, v1
	v_exp_f32_e32 v114, v2
	v_sub_f32_e32 v2, v37, v1
	v_exp_f32_e32 v115, v2
	v_sub_f32_e32 v2, v54, v1
	v_exp_f32_e32 v116, v2
	v_sub_f32_e32 v2, v38, v1
	v_exp_f32_e32 v117, v2
	v_sub_f32_e32 v2, v55, v1
	v_exp_f32_e32 v118, v2
	v_sub_f32_e32 v2, v39, v1
	v_exp_f32_e32 v119, v2
	v_sub_f32_e32 v2, v56, v1
	v_exp_f32_e32 v120, v2
	v_sub_f32_e32 v2, v40, v1
	v_exp_f32_e32 v121, v2
	v_sub_f32_e32 v2, v57, v1
	v_exp_f32_e32 v122, v2
	v_sub_f32_e32 v2, v41, v1
	v_exp_f32_e32 v123, v2
	v_sub_f32_e32 v2, v58, v1
	v_exp_f32_e32 v138, v2
	v_sub_f32_e32 v2, v42, v1
	v_exp_f32_e32 v139, v2
	v_sub_f32_e32 v2, v59, v1
	v_exp_f32_e32 v140, v2
	v_sub_f32_e32 v2, v43, v1
	v_exp_f32_e32 v141, v2
	v_sub_f32_e32 v2, v60, v1
	v_exp_f32_e32 v124, v2
	v_sub_f32_e32 v2, v44, v1
	v_exp_f32_e32 v125, v2
	v_sub_f32_e32 v2, v61, v1
	v_exp_f32_e32 v126, v2
	v_sub_f32_e32 v2, v45, v1
	v_add_f32_e32 v36, 0, v112
	v_add_f32_e32 v37, 0, v113
	v_exp_f32_e32 v127, v2
	v_sub_f32_e32 v2, v62, v1
	v_add_f32_e32 v36, v114, v36
	v_add_f32_e32 v37, v115, v37
	v_exp_f32_e32 v128, v2
	v_sub_f32_e32 v2, v46, v1
	v_add_f32_e32 v36, v116, v36
	v_add_f32_e32 v37, v117, v37
	v_exp_f32_e32 v129, v2
	v_sub_f32_e32 v2, v63, v1
	v_add_f32_e32 v36, v118, v36
	v_add_f32_e32 v37, v119, v37
	v_exp_f32_e32 v130, v2
	v_sub_f32_e32 v2, v47, v1
	v_add_f32_e32 v36, v120, v36
	v_add_f32_e32 v37, v121, v37
	v_exp_f32_e32 v131, v2
	v_sub_f32_e32 v2, v64, v1
	v_add_f32_e32 v36, v122, v36
	v_add_f32_e32 v37, v123, v37
	v_exp_f32_e32 v132, v2
	v_sub_f32_e32 v2, v48, v1
	v_exp_f32_e32 v133, v2
	v_sub_f32_e32 v2, v65, v1
	v_add_f32_e32 v36, v138, v36
	v_add_f32_e32 v37, v139, v37
	v_exp_f32_e32 v134, v2
	v_sub_f32_e32 v2, v49, v1
	v_add_f32_e32 v36, v140, v36
	v_add_f32_e32 v37, v141, v37
	v_exp_f32_e32 v135, v2
	v_sub_f32_e32 v2, v66, v1
	v_add_f32_e32 v36, v124, v36
	v_add_f32_e32 v37, v125, v37
	v_exp_f32_e32 v136, v2
	v_sub_f32_e32 v2, v50, v1
	v_add_f32_e32 v36, v126, v36
	v_add_f32_e32 v37, v127, v37
	v_exp_f32_e32 v137, v2
	v_add_f32_e32 v36, v128, v36
	v_add_f32_e32 v37, v129, v37
	v_exp_f32_e64 v164, -v1
	v_add_f32_e32 v36, v130, v36
	v_add_f32_e32 v37, v131, v37
	v_add_f32_e32 v161, v161, v1
	v_add_f32_e32 v36, v132, v36
	v_add_f32_e32 v37, v133, v37
	v_sub_f32_e32 v2, v67, v1
	v_add_f32_e32 v36, v134, v36
	v_add_f32_e32 v37, v135, v37
	v_sub_f32_e32 v1, v51, v1
	v_add_f32_e32 v46, v136, v36
	v_add_f32_e32 v47, v137, v37
	v_exp_f32_e32 v37, v1
	v_exp_f32_e32 v144, v2
	v_pk_mul_f32 v[18:19], v[18:19], v[164:165] op_sel_hi:[1,0]
	v_pk_mul_f32 v[16:17], v[16:17], v[164:165] op_sel_hi:[1,0]
	v_mov_b32_e32 v145, v37
	v_pk_mul_f32 v[14:15], v[14:15], v[164:165] op_sel_hi:[1,0]
	v_pk_mul_f32 v[12:13], v[12:13], v[164:165] op_sel_hi:[1,0]
	v_pk_mul_f32 v[10:11], v[10:11], v[164:165] op_sel_hi:[1,0]
	v_pk_mul_f32 v[8:9], v[8:9], v[164:165] op_sel_hi:[1,0]
	v_pk_mul_f32 v[6:7], v[6:7], v[164:165] op_sel_hi:[1,0]
	v_pk_mul_f32 v[4:5], v[4:5], v[164:165] op_sel_hi:[1,0]
	v_mov_b32_e32 v2, v113
	v_mov_b32_e32 v1, v115
	v_mov_b32_e32 v42, v117
	v_mov_b32_e32 v45, v119
	v_mov_b32_e32 v38, v121
	v_mov_b32_e32 v41, v123
	v_mov_b32_e32 v40, v139
	v_mov_b32_e32 v43, v141
	v_mov_b32_e32 v36, v125
	v_mov_b32_e32 v39, v127
	v_add_f32_e32 v142, v144, v46
	v_add_f32_e32 v143, v145, v47
	v_pk_mul_f32 v[34:35], v[34:35], v[164:165] op_sel_hi:[1,0]
	v_pk_mul_f32 v[32:33], v[32:33], v[164:165] op_sel_hi:[1,0]
	v_pk_mul_f32 v[30:31], v[30:31], v[164:165] op_sel_hi:[1,0]
	v_pk_mul_f32 v[28:29], v[28:29], v[164:165] op_sel_hi:[1,0]
	v_pk_mul_f32 v[26:27], v[26:27], v[164:165] op_sel_hi:[1,0]
	v_pk_mul_f32 v[24:25], v[24:25], v[164:165] op_sel_hi:[1,0]
	v_pk_mul_f32 v[22:23], v[22:23], v[164:165] op_sel_hi:[1,0]
	v_pk_mul_f32 v[20:21], v[20:21], v[164:165] op_sel_hi:[1,0]
	v_mul_f32_e32 v149, v149, v164
	v_mov_b32_e32 v44, v129
	v_mov_b32_e32 v47, v131
	v_mov_b32_e32 v46, v133
	v_mov_b32_e32 v49, v135
	v_mov_b32_e32 v48, v137
	s_branch .LBB0_417
